# gate/up last-round tile sharing: also skip the foreign half's A-fragment LDS reads
# baseline (speedup 1.0000x reference)
.LBB0_41:
	s_add_u32 s40, s36, 0xfffc0080
	s_addc_u32 s41, s37, -1
	s_add_i32 s97, 0, 0x10000
	s_cmp_eq_u32 s90, 12
	s_cselect_b32 s47, s17, s41
	s_cselect_b32 s46, s68, s40
	v_add_u32_e32 v140, s97, v142
	s_cselect_b32 s45, s15, s89
	s_cselect_b32 s44, s69, s88
	s_add_i32 s40, 0, 0x14000
	ds_read_b128 v[146:149], v140
	ds_read_b128 v[150:153], v140 offset:1024
	ds_read_b128 v[154:157], v140 offset:2048
	ds_read_b128 v[158:161], v140 offset:3072
	v_add_u32_e32 v140, s40, v142
	ds_read_b128 v[162:165], v140
	ds_read_b128 v[166:169], v140 offset:1024
	ds_read_b128 v[170:173], v140 offset:2048
	ds_read_b128 v[174:177], v140 offset:3072
	v_lshl_add_u64 v[140:141], s[36:37], 0, v[136:137]
	s_add_i32 m0, s51, 0xc000
	s_cmp_eq_u32 s100, 2
	s_cbranch_scc1 .Lht_rd0
	ds_read_b128 v[190:193], v145
	ds_read_b128 v[194:197], v145 offset:1024
	ds_read_b128 v[198:201], v145 offset:2048
	ds_read_b128 v[202:205], v145 offset:3072
	ds_read_b128 v[206:209], v145 offset:4096
	ds_read_b128 v[228:231], v145 offset:5120
	ds_read_b128 v[232:235], v145 offset:6144
	ds_read_b128 v[236:239], v145 offset:7168
.Lht_rd0:
	global_load_lds_dwordx4 v[140:141], off
	v_lshl_add_u64 v[140:141], s[36:37], 0, v[138:139]
	s_add_i32 m0, s51, 0xe000
	s_nop 0
	global_load_lds_dwordx4 v[140:141], off
	s_waitcnt vmcnt(8)
	s_waitcnt lgkmcnt(0)
	s_barrier
	s_setprio 1
	s_waitcnt lgkmcnt(0)
	s_cmp_eq_u32 s100, 2
	s_cbranch_scc1 .Lht_mma0
	v_mfma_f32_16x16x32_bf16 v[124:127], v[146:149], v[190:193], v[124:127]
	v_mfma_f32_16x16x32_bf16 v[116:119], v[154:157], v[190:193], v[116:119]
	v_mfma_f32_16x16x32_bf16 v[108:111], v[146:149], v[198:201], v[108:111]
	v_mfma_f32_16x16x32_bf16 v[100:103], v[154:157], v[198:201], v[100:103]
	v_mfma_f32_16x16x32_bf16 v[92:95], v[146:149], v[206:209], v[92:95]
	v_mfma_f32_16x16x32_bf16 v[84:87], v[154:157], v[206:209], v[84:87]
	v_mfma_f32_16x16x32_bf16 v[76:79], v[146:149], v[232:235], v[76:79]
	v_mfma_f32_16x16x32_bf16 v[68:71], v[154:157], v[232:235], v[68:71]
	v_mfma_f32_16x16x32_bf16 v[124:127], v[150:153], v[194:197], v[124:127]
	v_mfma_f32_16x16x32_bf16 v[116:119], v[158:161], v[194:197], v[116:119]
	v_mfma_f32_16x16x32_bf16 v[108:111], v[150:153], v[202:205], v[108:111]
	v_mfma_f32_16x16x32_bf16 v[100:103], v[158:161], v[202:205], v[100:103]
	v_mfma_f32_16x16x32_bf16 v[92:95], v[150:153], v[228:231], v[92:95]
	v_mfma_f32_16x16x32_bf16 v[84:87], v[158:161], v[228:231], v[84:87]
	v_mfma_f32_16x16x32_bf16 v[76:79], v[150:153], v[236:239], v[76:79]
	v_mfma_f32_16x16x32_bf16 v[68:71], v[158:161], v[236:239], v[68:71]
	s_setprio 0
	s_setprio 1
	v_mfma_f32_16x16x32_bf16 v[128:131], v[162:165], v[190:193], v[128:131]
	v_mfma_f32_16x16x32_bf16 v[120:123], v[170:173], v[190:193], v[120:123]
	v_mfma_f32_16x16x32_bf16 v[112:115], v[162:165], v[198:201], v[112:115]
	v_mfma_f32_16x16x32_bf16 v[104:107], v[170:173], v[198:201], v[104:107]
	v_mfma_f32_16x16x32_bf16 v[96:99], v[162:165], v[206:209], v[96:99]
	v_mfma_f32_16x16x32_bf16 v[88:91], v[170:173], v[206:209], v[88:91]
	v_mfma_f32_16x16x32_bf16 v[80:83], v[162:165], v[232:235], v[80:83]
	v_mfma_f32_16x16x32_bf16 v[72:75], v[170:173], v[232:235], v[72:75]
	v_mfma_f32_16x16x32_bf16 v[128:131], v[166:169], v[194:197], v[128:131]
	v_mfma_f32_16x16x32_bf16 v[120:123], v[174:177], v[194:197], v[120:123]
	v_mfma_f32_16x16x32_bf16 v[112:115], v[166:169], v[202:205], v[112:115]
	v_mfma_f32_16x16x32_bf16 v[104:107], v[174:177], v[202:205], v[104:107]
	v_mfma_f32_16x16x32_bf16 v[96:99], v[166:169], v[228:231], v[96:99]
	v_mfma_f32_16x16x32_bf16 v[88:91], v[174:177], v[228:231], v[88:91]
	v_mfma_f32_16x16x32_bf16 v[80:83], v[166:169], v[236:239], v[80:83]
	v_mfma_f32_16x16x32_bf16 v[72:75], v[174:177], v[236:239], v[72:75]
.Lht_mma0:
	s_setprio 0
	s_barrier
	s_add_i32 s41, s97, s50
	v_lshl_add_u64 v[140:141], s[44:45], 0, v[180:181]
	s_mov_b32 m0, s41
	s_cmp_eq_u32 s100, 1
	s_cbranch_scc1 .Lht_rd1
	ds_read_b128 v[190:193], v145 offset:16384
	ds_read_b128 v[194:197], v145 offset:17408
	ds_read_b128 v[198:201], v145 offset:18432
	ds_read_b128 v[202:205], v145 offset:19456
	ds_read_b128 v[206:209], v145 offset:20480
	ds_read_b128 v[228:231], v145 offset:21504
	ds_read_b128 v[232:235], v145 offset:22528
	ds_read_b128 v[236:239], v145 offset:23552
.Lht_rd1:
	global_load_lds_dwordx4 v[140:141], off
	s_add_i32 m0, s41, 0x2000
	s_add_u32 vcc_lo, s44, 0x40000
	v_lshl_add_u64 v[178:179], s[44:45], 0, v[134:135]
	s_addc_u32 vcc_hi, s45, 0
	s_add_i32 s40, s40, s50
	global_load_lds_dwordx4 v[178:179], off
	v_lshl_add_u64 v[210:211], vcc, 0, v[180:181]
	s_mov_b32 m0, s40
	v_lshl_add_u64 v[218:219], s[46:47], 0, v[132:133]
	global_load_lds_dwordx4 v[210:211], off
	v_lshl_add_u64 v[210:211], vcc, 0, v[134:135]
	s_add_i32 m0, s40, 0x2000
	s_nop 0
	global_load_lds_dwordx4 v[210:211], off
	v_lshl_add_u64 v[210:211], s[46:47], 0, v[0:1]
	s_mov_b32 m0, s51
	s_nop 0
	global_load_lds_dwordx4 v[210:211], off
	s_mov_b32 m0, s52
	s_nop 0
	global_load_lds_dwordx4 v[218:219], off
	s_waitcnt vmcnt(8)
	s_waitcnt lgkmcnt(0)
	s_barrier
	s_setprio 1
	s_waitcnt lgkmcnt(0)
	s_cmp_eq_u32 s100, 1
	s_cbranch_scc1 .Lht_mma1
	v_mfma_f32_16x16x32_bf16 v[60:63], v[146:149], v[190:193], v[60:63]
	v_mfma_f32_16x16x32_bf16 v[52:55], v[154:157], v[190:193], v[52:55]
	v_mfma_f32_16x16x32_bf16 v[44:47], v[146:149], v[198:201], v[44:47]
	v_mfma_f32_16x16x32_bf16 v[36:39], v[154:157], v[198:201], v[36:39]
	v_mfma_f32_16x16x32_bf16 v[28:31], v[146:149], v[206:209], v[28:31]
	v_mfma_f32_16x16x32_bf16 v[20:23], v[154:157], v[206:209], v[20:23]
	v_mfma_f32_16x16x32_bf16 v[12:15], v[146:149], v[232:235], v[12:15]
	v_mfma_f32_16x16x32_bf16 v[8:11], v[154:157], v[232:235], v[8:11]
	v_mfma_f32_16x16x32_bf16 v[60:63], v[150:153], v[194:197], v[60:63]
	v_mfma_f32_16x16x32_bf16 v[52:55], v[158:161], v[194:197], v[52:55]
	v_mfma_f32_16x16x32_bf16 v[44:47], v[150:153], v[202:205], v[44:47]
	v_mfma_f32_16x16x32_bf16 v[36:39], v[158:161], v[202:205], v[36:39]
	v_mfma_f32_16x16x32_bf16 v[28:31], v[150:153], v[228:231], v[28:31]
	v_mfma_f32_16x16x32_bf16 v[20:23], v[158:161], v[228:231], v[20:23]
	v_mfma_f32_16x16x32_bf16 v[12:15], v[150:153], v[236:239], v[12:15]
	v_mfma_f32_16x16x32_bf16 v[8:11], v[158:161], v[236:239], v[8:11]
	s_setprio 0
	s_setprio 1
	v_mfma_f32_16x16x32_bf16 v[64:67], v[162:165], v[190:193], v[64:67]
	v_mfma_f32_16x16x32_bf16 v[56:59], v[170:173], v[190:193], v[56:59]
	v_mfma_f32_16x16x32_bf16 v[48:51], v[162:165], v[198:201], v[48:51]
	v_mfma_f32_16x16x32_bf16 v[40:43], v[170:173], v[198:201], v[40:43]
	v_mfma_f32_16x16x32_bf16 v[32:35], v[162:165], v[206:209], v[32:35]
	v_mfma_f32_16x16x32_bf16 v[24:27], v[170:173], v[206:209], v[24:27]
	v_mfma_f32_16x16x32_bf16 v[16:19], v[162:165], v[232:235], v[16:19]
	v_mfma_f32_16x16x32_bf16 v[4:7], v[170:173], v[232:235], v[4:7]
	v_mfma_f32_16x16x32_bf16 v[64:67], v[166:169], v[194:197], v[64:67]
	v_mfma_f32_16x16x32_bf16 v[56:59], v[174:177], v[194:197], v[56:59]
	v_mfma_f32_16x16x32_bf16 v[48:51], v[166:169], v[202:205], v[48:51]
	v_mfma_f32_16x16x32_bf16 v[40:43], v[174:177], v[202:205], v[40:43]
	v_mfma_f32_16x16x32_bf16 v[32:35], v[166:169], v[228:231], v[32:35]
	v_mfma_f32_16x16x32_bf16 v[24:27], v[174:177], v[228:231], v[24:27]
	v_mfma_f32_16x16x32_bf16 v[16:19], v[166:169], v[236:239], v[16:19]
	v_mfma_f32_16x16x32_bf16 v[4:7], v[174:177], v[236:239], v[4:7]
.Lht_mma1:
	s_setprio 0
	s_barrier
	s_add_i32 s40, 0, 0x18000
	s_add_i32 s41, 0, 0x1c000
	v_add_u32_e32 v158, s40, v142
	v_add_u32_e32 v174, s41, v142
	ds_read_b128 v[146:149], v158
	ds_read_b128 v[150:153], v158 offset:1024
	ds_read_b128 v[154:157], v158 offset:2048
	ds_read_b128 v[158:161], v158 offset:3072
	ds_read_b128 v[162:165], v174
	ds_read_b128 v[166:169], v174 offset:1024
	ds_read_b128 v[170:173], v174 offset:2048
	ds_read_b128 v[174:177], v174 offset:3072
	s_add_u32 s46, s46, 0x40000
	s_addc_u32 s47, s47, 0
	s_mov_b32 m0, s53
	v_lshl_add_u64 v[220:221], s[46:47], 0, v[0:1]
	s_cmp_eq_u32 s100, 2
	s_cbranch_scc1 .Lht_rd2
	ds_read_b128 v[190:193], v145 offset:32768
	ds_read_b128 v[194:197], v145 offset:33792
	ds_read_b128 v[198:201], v145 offset:34816
	ds_read_b128 v[202:205], v145 offset:35840
	ds_read_b128 v[206:209], v145 offset:36864
	ds_read_b128 v[228:231], v145 offset:37888
	ds_read_b128 v[232:235], v145 offset:38912
	ds_read_b128 v[236:239], v145 offset:39936
.Lht_rd2:
	global_load_lds_dwordx4 v[220:221], off
	v_lshl_add_u64 v[220:221], s[46:47], 0, v[132:133]
	s_mov_b32 m0, s54
	s_nop 0
	global_load_lds_dwordx4 v[220:221], off
	s_waitcnt vmcnt(8)
	s_waitcnt lgkmcnt(0)
	s_barrier
	s_setprio 1
	s_waitcnt lgkmcnt(0)
	s_cmp_eq_u32 s100, 2
	s_cbranch_scc1 .Lht_mma2
	v_mfma_f32_16x16x32_bf16 v[124:127], v[146:149], v[190:193], v[124:127]
	v_mfma_f32_16x16x32_bf16 v[116:119], v[154:157], v[190:193], v[116:119]
	v_mfma_f32_16x16x32_bf16 v[108:111], v[146:149], v[198:201], v[108:111]
	v_mfma_f32_16x16x32_bf16 v[100:103], v[154:157], v[198:201], v[100:103]
	v_mfma_f32_16x16x32_bf16 v[92:95], v[146:149], v[206:209], v[92:95]
	v_mfma_f32_16x16x32_bf16 v[84:87], v[154:157], v[206:209], v[84:87]
	v_mfma_f32_16x16x32_bf16 v[76:79], v[146:149], v[232:235], v[76:79]
	v_mfma_f32_16x16x32_bf16 v[68:71], v[154:157], v[232:235], v[68:71]
	v_mfma_f32_16x16x32_bf16 v[124:127], v[150:153], v[194:197], v[124:127]
	v_mfma_f32_16x16x32_bf16 v[116:119], v[158:161], v[194:197], v[116:119]
	v_mfma_f32_16x16x32_bf16 v[108:111], v[150:153], v[202:205], v[108:111]
	v_mfma_f32_16x16x32_bf16 v[100:103], v[158:161], v[202:205], v[100:103]
	v_mfma_f32_16x16x32_bf16 v[92:95], v[150:153], v[228:231], v[92:95]
	v_mfma_f32_16x16x32_bf16 v[84:87], v[158:161], v[228:231], v[84:87]
	v_mfma_f32_16x16x32_bf16 v[76:79], v[150:153], v[236:239], v[76:79]
	v_mfma_f32_16x16x32_bf16 v[68:71], v[158:161], v[236:239], v[68:71]
	s_setprio 0
	s_setprio 1
	v_mfma_f32_16x16x32_bf16 v[128:131], v[162:165], v[190:193], v[128:131]
	v_mfma_f32_16x16x32_bf16 v[120:123], v[170:173], v[190:193], v[120:123]
	v_mfma_f32_16x16x32_bf16 v[112:115], v[162:165], v[198:201], v[112:115]
	v_mfma_f32_16x16x32_bf16 v[104:107], v[170:173], v[198:201], v[104:107]
	v_mfma_f32_16x16x32_bf16 v[96:99], v[162:165], v[206:209], v[96:99]
	v_mfma_f32_16x16x32_bf16 v[88:91], v[170:173], v[206:209], v[88:91]
	v_mfma_f32_16x16x32_bf16 v[80:83], v[162:165], v[232:235], v[80:83]
	v_mfma_f32_16x16x32_bf16 v[72:75], v[170:173], v[232:235], v[72:75]
	v_mfma_f32_16x16x32_bf16 v[128:131], v[166:169], v[194:197], v[128:131]
	v_mfma_f32_16x16x32_bf16 v[120:123], v[174:177], v[194:197], v[120:123]
	v_mfma_f32_16x16x32_bf16 v[112:115], v[166:169], v[202:205], v[112:115]
	v_mfma_f32_16x16x32_bf16 v[104:107], v[174:177], v[202:205], v[104:107]
	v_mfma_f32_16x16x32_bf16 v[96:99], v[166:169], v[228:231], v[96:99]
	v_mfma_f32_16x16x32_bf16 v[88:91], v[174:177], v[228:231], v[88:91]
	v_mfma_f32_16x16x32_bf16 v[80:83], v[166:169], v[236:239], v[80:83]
	v_mfma_f32_16x16x32_bf16 v[72:75], v[174:177], v[236:239], v[72:75]
.Lht_mma2:
	s_setprio 0
	s_barrier
	s_add_i32 s40, s40, s50
	v_lshl_add_u64 v[140:141], v[140:141], 0, s[94:95]
	s_mov_b32 m0, s40
	s_cmp_eq_u32 s100, 1
	s_cbranch_scc1 .Lht_rd3
	ds_read_b128 v[190:193], v145 offset:49152
	ds_read_b128 v[194:197], v145 offset:50176
	ds_read_b128 v[198:201], v145 offset:51200
	ds_read_b128 v[202:205], v145 offset:52224
	ds_read_b128 v[206:209], v145 offset:53248
	ds_read_b128 v[228:231], v145 offset:54272
	ds_read_b128 v[232:235], v145 offset:55296
	ds_read_b128 v[236:239], v145 offset:56320
.Lht_rd3:
	global_load_lds_dwordx4 v[140:141], off
	s_add_i32 m0, s40, 0x2000
	s_add_u32 s44, s44, 0x40080
	v_lshl_add_u64 v[140:141], v[178:179], 0, s[94:95]
	s_addc_u32 s45, s45, 0
	s_add_i32 s40, s41, s50
	global_load_lds_dwordx4 v[140:141], off
	v_lshl_add_u64 v[140:141], s[44:45], 0, v[180:181]
	s_mov_b32 m0, s40
	s_nop 0
	global_load_lds_dwordx4 v[140:141], off
	v_lshl_add_u64 v[140:141], s[44:45], 0, v[134:135]
	s_add_i32 m0, s40, 0x2000
	s_nop 0
	global_load_lds_dwordx4 v[140:141], off
	v_lshl_add_u64 v[140:141], v[210:211], 0, s[94:95]
	s_mov_b32 m0, s55
	s_nop 0
	global_load_lds_dwordx4 v[140:141], off
	v_lshl_add_u64 v[140:141], v[218:219], 0, s[94:95]
	s_mov_b32 m0, s58
	s_nop 0
	global_load_lds_dwordx4 v[140:141], off
	s_waitcnt vmcnt(8)
	s_waitcnt lgkmcnt(0)
	s_barrier
	s_setprio 1
	s_waitcnt lgkmcnt(0)
	s_cmp_eq_u32 s100, 1
	s_cbranch_scc1 .Lht_mma3
	v_mfma_f32_16x16x32_bf16 v[60:63], v[146:149], v[190:193], v[60:63]
	v_mfma_f32_16x16x32_bf16 v[52:55], v[154:157], v[190:193], v[52:55]
	v_mfma_f32_16x16x32_bf16 v[44:47], v[146:149], v[198:201], v[44:47]
	v_mfma_f32_16x16x32_bf16 v[36:39], v[154:157], v[198:201], v[36:39]
	v_mfma_f32_16x16x32_bf16 v[28:31], v[146:149], v[206:209], v[28:31]
	v_mfma_f32_16x16x32_bf16 v[20:23], v[154:157], v[206:209], v[20:23]
	v_mfma_f32_16x16x32_bf16 v[12:15], v[146:149], v[232:235], v[12:15]
	v_mfma_f32_16x16x32_bf16 v[8:11], v[154:157], v[232:235], v[8:11]
	v_mfma_f32_16x16x32_bf16 v[60:63], v[150:153], v[194:197], v[60:63]
	v_mfma_f32_16x16x32_bf16 v[52:55], v[158:161], v[194:197], v[52:55]
	v_mfma_f32_16x16x32_bf16 v[44:47], v[150:153], v[202:205], v[44:47]
	v_mfma_f32_16x16x32_bf16 v[36:39], v[158:161], v[202:205], v[36:39]
	v_mfma_f32_16x16x32_bf16 v[28:31], v[150:153], v[228:231], v[28:31]
	v_mfma_f32_16x16x32_bf16 v[20:23], v[158:161], v[228:231], v[20:23]
	v_mfma_f32_16x16x32_bf16 v[12:15], v[150:153], v[236:239], v[12:15]
	v_mfma_f32_16x16x32_bf16 v[8:11], v[158:161], v[236:239], v[8:11]
	s_setprio 0
	s_setprio 1
	v_mfma_f32_16x16x32_bf16 v[64:67], v[162:165], v[190:193], v[64:67]
	v_mfma_f32_16x16x32_bf16 v[56:59], v[170:173], v[190:193], v[56:59]
	v_mfma_f32_16x16x32_bf16 v[48:51], v[162:165], v[198:201], v[48:51]
	v_mfma_f32_16x16x32_bf16 v[40:43], v[170:173], v[198:201], v[40:43]
	v_mfma_f32_16x16x32_bf16 v[32:35], v[162:165], v[206:209], v[32:35]
	v_mfma_f32_16x16x32_bf16 v[24:27], v[170:173], v[206:209], v[24:27]
	v_mfma_f32_16x16x32_bf16 v[16:19], v[162:165], v[232:235], v[16:19]
	v_mfma_f32_16x16x32_bf16 v[4:7], v[170:173], v[232:235], v[4:7]
	v_mfma_f32_16x16x32_bf16 v[64:67], v[166:169], v[194:197], v[64:67]
	v_mfma_f32_16x16x32_bf16 v[56:59], v[174:177], v[194:197], v[56:59]
	v_mfma_f32_16x16x32_bf16 v[48:51], v[166:169], v[202:205], v[48:51]
	v_mfma_f32_16x16x32_bf16 v[40:43], v[174:177], v[202:205], v[40:43]
	v_mfma_f32_16x16x32_bf16 v[32:35], v[166:169], v[228:231], v[32:35]
	v_mfma_f32_16x16x32_bf16 v[24:27], v[174:177], v[228:231], v[24:27]
	v_mfma_f32_16x16x32_bf16 v[16:19], v[166:169], v[236:239], v[16:19]
	v_mfma_f32_16x16x32_bf16 v[4:7], v[174:177], v[236:239], v[4:7]
